# LayerNorm phases: per-column vector staging via LDS-DMA (up to 16 global_load_lds in flight, one wait) instead of the serialized load/wait/ds_write loop; on top of astat MFMA order + unscaled MFMA + h
# speedup vs baseline: 1.0085x; 1.0030x over previous
.LBB0_123:
	s_waitcnt lgkmcnt(0)
	v_readlane_b32 s98, v254, 13
	v_lshlrev_b32_e32 v36, 4, v0
	v_add_u32_e32 v37, 0x2000, v36
	s_lshl_b32 s98, s98, 10
	s_mov_b32 s100, s92
	s_mov_b32 s101, s93
	s_add_i32 s99, s98, 0x8000
	s_mov_b32 m0, s99
	s_nop 0
	global_load_lds_dwordx4 v36, s[100:101]
	s_mov_b32 s100, s92
	s_mov_b32 s101, s93
	s_add_i32 s99, s98, 0xa000
	s_mov_b32 m0, s99
	s_nop 0
	global_load_lds_dwordx4 v37, s[100:101]
	s_add_u32 s100, s92, 0x4000
	s_addc_u32 s101, s93, 0
	s_add_i32 s99, s98, 0xc000
	s_mov_b32 m0, s99
	s_nop 0
	global_load_lds_dwordx4 v36, s[100:101]
	s_add_u32 s100, s92, 0x4000
	s_addc_u32 s101, s93, 0
	s_add_i32 s99, s98, 0xe000
	s_mov_b32 m0, s99
	s_nop 0
	global_load_lds_dwordx4 v37, s[100:101]
	s_add_u32 s100, s92, 0x24000
	s_addc_u32 s101, s93, 0
	s_add_i32 s99, s98, 0x10000
	s_mov_b32 m0, s99
	s_nop 0
	global_load_lds_dwordx4 v36, s[100:101]
	s_add_u32 s100, s92, 0x24000
	s_addc_u32 s101, s93, 0
	s_add_i32 s99, s98, 0x12000
	s_mov_b32 m0, s99
	s_nop 0
	global_load_lds_dwordx4 v37, s[100:101]
	s_add_u32 s100, s92, 0x28000
	s_addc_u32 s101, s93, 0
	s_add_i32 s99, s98, 0x14000
	s_mov_b32 m0, s99
	s_nop 0
	global_load_lds_dwordx4 v36, s[100:101]
	s_add_u32 s100, s92, 0x28000
	s_addc_u32 s101, s93, 0
	s_add_i32 s99, s98, 0x16000
	s_mov_b32 m0, s99
	s_nop 0
	global_load_lds_dwordx4 v37, s[100:101]
	s_add_u32 s100, s92, 0x48000
	s_addc_u32 s101, s93, 0
	s_add_i32 s99, s98, 0x18000
	s_mov_b32 m0, s99
	s_nop 0
	global_load_lds_dwordx4 v36, s[100:101]
	s_add_u32 s100, s92, 0x48000
	s_addc_u32 s101, s93, 0
	s_add_i32 s99, s98, 0x1a000
	s_mov_b32 m0, s99
	s_nop 0
	global_load_lds_dwordx4 v37, s[100:101]
	s_add_u32 s100, s92, 0x4c000
	s_addc_u32 s101, s93, 0
	s_add_i32 s99, s98, 0x1c000
	s_mov_b32 m0, s99
	s_nop 0
	global_load_lds_dwordx4 v36, s[100:101]
	s_add_u32 s100, s92, 0x4c000
	s_addc_u32 s101, s93, 0
	s_add_i32 s99, s98, 0x1e000
	s_mov_b32 m0, s99
	s_nop 0
	global_load_lds_dwordx4 v37, s[100:101]
	s_waitcnt vmcnt(0)
	s_mov_b64 s[4:5], -1

.LBB0_350:
.LBB0_351:
	s_waitcnt lgkmcnt(0)
	v_readlane_b32 s98, v254, 13
	v_lshlrev_b32_e32 v68, 4, v0
	v_add_u32_e32 v69, 0x2000, v68
	s_lshl_b32 s98, s98, 10
	s_mov_b32 s100, s58
	s_mov_b32 s101, s59
	s_add_i32 s99, s98, 0x0
	s_mov_b32 m0, s99
	s_nop 0
	global_load_lds_dwordx4 v68, s[100:101]
	s_mov_b32 s100, s58
	s_mov_b32 s101, s59
	s_add_i32 s99, s98, 0x2000
	s_mov_b32 m0, s99
	s_nop 0
	global_load_lds_dwordx4 v69, s[100:101]
	s_mov_b32 s100, s28
	s_mov_b32 s101, s29
	s_add_i32 s99, s98, 0x4000
	s_mov_b32 m0, s99
	s_nop 0
	global_load_lds_dwordx4 v68, s[100:101]
	s_mov_b32 s100, s28
	s_mov_b32 s101, s29
	s_add_i32 s99, s98, 0x6000
	s_mov_b32 m0, s99
	s_nop 0
	global_load_lds_dwordx4 v69, s[100:101]
	s_add_u32 s100, s92, 0xc000
	s_addc_u32 s101, s93, 0
	s_add_i32 s99, s98, 0x8000
	s_mov_b32 m0, s99
	s_nop 0
	global_load_lds_dwordx4 v68, s[100:101]
	s_add_u32 s100, s92, 0xc000
	s_addc_u32 s101, s93, 0
	s_add_i32 s99, s98, 0xa000
	s_mov_b32 m0, s99
	s_nop 0
	global_load_lds_dwordx4 v69, s[100:101]
	s_add_u32 s100, s92, 0x10000
	s_addc_u32 s101, s93, 0
	s_add_i32 s99, s98, 0xc000
	s_mov_b32 m0, s99
	s_nop 0
	global_load_lds_dwordx4 v68, s[100:101]
	s_add_u32 s100, s92, 0x10000
	s_addc_u32 s101, s93, 0
	s_add_i32 s99, s98, 0xe000
	s_mov_b32 m0, s99
	s_nop 0
	global_load_lds_dwordx4 v69, s[100:101]
	s_add_u32 s100, s92, 0x30000
	s_addc_u32 s101, s93, 0
	s_add_i32 s99, s98, 0x10000
	s_mov_b32 m0, s99
	s_nop 0
	global_load_lds_dwordx4 v68, s[100:101]
	s_add_u32 s100, s92, 0x30000
	s_addc_u32 s101, s93, 0
	s_add_i32 s99, s98, 0x12000
	s_mov_b32 m0, s99
	s_nop 0
	global_load_lds_dwordx4 v69, s[100:101]
	s_add_u32 s100, s92, 0x34000
	s_addc_u32 s101, s93, 0
	s_add_i32 s99, s98, 0x14000
	s_mov_b32 m0, s99
	s_nop 0
	global_load_lds_dwordx4 v68, s[100:101]
	s_add_u32 s100, s92, 0x34000
	s_addc_u32 s101, s93, 0
	s_add_i32 s99, s98, 0x16000
	s_mov_b32 m0, s99
	s_nop 0
	global_load_lds_dwordx4 v69, s[100:101]
	s_add_u32 s100, s92, 0x54000
	s_addc_u32 s101, s93, 0
	s_add_i32 s99, s98, 0x18000
	s_mov_b32 m0, s99
	s_nop 0
	global_load_lds_dwordx4 v68, s[100:101]
	s_add_u32 s100, s92, 0x54000
	s_addc_u32 s101, s93, 0
	s_add_i32 s99, s98, 0x1a000
	s_mov_b32 m0, s99
	s_nop 0
	global_load_lds_dwordx4 v69, s[100:101]
	s_add_u32 s100, s92, 0x58000
	s_addc_u32 s101, s93, 0
	s_add_i32 s99, s98, 0x1c000
	s_mov_b32 m0, s99
	s_nop 0
	global_load_lds_dwordx4 v68, s[100:101]
	s_add_u32 s100, s92, 0x58000
	s_addc_u32 s101, s93, 0
	s_add_i32 s99, s98, 0x1e000
	s_mov_b32 m0, s99
	s_nop 0
	global_load_lds_dwordx4 v69, s[100:101]
	s_waitcnt vmcnt(0)
	s_mov_b64 s[2:3], -1

.LBB0_859:
.LBB0_860:
	s_add_u32 s2, s58, 0x4000
	s_addc_u32 s3, s59, 0
	s_add_u32 s4, s28, 0x4000
	s_addc_u32 s5, s29, 0
	s_waitcnt lgkmcnt(0)
	v_readlane_b32 s98, v254, 13
	v_lshlrev_b32_e32 v68, 4, v0
	v_add_u32_e32 v69, 0x2000, v68
	s_lshl_b32 s98, s98, 10
	s_add_u32 s100, s58, 0x4000
	s_addc_u32 s101, s59, 0
	s_add_i32 s99, s98, 0x0
	s_mov_b32 m0, s99
	s_nop 0
	global_load_lds_dwordx4 v68, s[100:101]
	s_add_u32 s100, s58, 0x4000
	s_addc_u32 s101, s59, 0
	s_add_i32 s99, s98, 0x2000
	s_mov_b32 m0, s99
	s_nop 0
	global_load_lds_dwordx4 v69, s[100:101]
	s_add_u32 s100, s28, 0x4000
	s_addc_u32 s101, s29, 0
	s_add_i32 s99, s98, 0x4000
	s_mov_b32 m0, s99
	s_nop 0
	global_load_lds_dwordx4 v68, s[100:101]
	s_add_u32 s100, s28, 0x4000
	s_addc_u32 s101, s29, 0
	s_add_i32 s99, s98, 0x6000
	s_mov_b32 m0, s99
	s_nop 0
	global_load_lds_dwordx4 v69, s[100:101]
	s_add_u32 s100, s92, 0x18000
	s_addc_u32 s101, s93, 0
	s_add_i32 s99, s98, 0x8000
	s_mov_b32 m0, s99
	s_nop 0
	global_load_lds_dwordx4 v68, s[100:101]
	s_add_u32 s100, s92, 0x18000
	s_addc_u32 s101, s93, 0
	s_add_i32 s99, s98, 0xa000
	s_mov_b32 m0, s99
	s_nop 0
	global_load_lds_dwordx4 v69, s[100:101]
	s_add_u32 s100, s92, 0x1c000
	s_addc_u32 s101, s93, 0
	s_add_i32 s99, s98, 0xc000
	s_mov_b32 m0, s99
	s_nop 0
	global_load_lds_dwordx4 v68, s[100:101]
	s_add_u32 s100, s92, 0x1c000
	s_addc_u32 s101, s93, 0
	s_add_i32 s99, s98, 0xe000
	s_mov_b32 m0, s99
	s_nop 0
	global_load_lds_dwordx4 v69, s[100:101]
	s_add_u32 s100, s92, 0x3c000
	s_addc_u32 s101, s93, 0
	s_add_i32 s99, s98, 0x10000
	s_mov_b32 m0, s99
	s_nop 0
	global_load_lds_dwordx4 v68, s[100:101]
	s_add_u32 s100, s92, 0x3c000
	s_addc_u32 s101, s93, 0
	s_add_i32 s99, s98, 0x12000
	s_mov_b32 m0, s99
	s_nop 0
	global_load_lds_dwordx4 v69, s[100:101]
	s_add_u32 s100, s92, 0x40000
	s_addc_u32 s101, s93, 0
	s_add_i32 s99, s98, 0x14000
	s_mov_b32 m0, s99
	s_nop 0
	global_load_lds_dwordx4 v68, s[100:101]
	s_add_u32 s100, s92, 0x40000
	s_addc_u32 s101, s93, 0
	s_add_i32 s99, s98, 0x16000
	s_mov_b32 m0, s99
	s_nop 0
	global_load_lds_dwordx4 v69, s[100:101]
	s_add_u32 s100, s92, 0x60000
	s_addc_u32 s101, s93, 0
	s_add_i32 s99, s98, 0x18000
	s_mov_b32 m0, s99
	s_nop 0
	global_load_lds_dwordx4 v68, s[100:101]
	s_add_u32 s100, s92, 0x60000
	s_addc_u32 s101, s93, 0
	s_add_i32 s99, s98, 0x1a000
	s_mov_b32 m0, s99
	s_nop 0
	global_load_lds_dwordx4 v69, s[100:101]
	s_add_u32 s100, s92, 0x64000
	s_addc_u32 s101, s93, 0
	s_add_i32 s99, s98, 0x1c000
	s_mov_b32 m0, s99
	s_nop 0
	global_load_lds_dwordx4 v68, s[100:101]
	s_add_u32 s100, s92, 0x64000
	s_addc_u32 s101, s93, 0
	s_add_i32 s99, s98, 0x1e000
	s_mov_b32 m0, s99
	s_nop 0
	global_load_lds_dwordx4 v69, s[100:101]
	s_waitcnt vmcnt(0)
	s_mov_b64 s[6:7], -1

.LBB0_1099:
.LBB0_1100:
	s_add_u32 s2, s58, 0x8000
	s_addc_u32 s3, s59, 0
	s_add_u32 s4, s28, 0x8000
	s_addc_u32 s5, s29, 0
	s_waitcnt lgkmcnt(0)
	v_readlane_b32 s98, v254, 13
	v_lshlrev_b32_e32 v68, 4, v0
	v_add_u32_e32 v69, 0x2000, v68
	s_lshl_b32 s98, s98, 10
	s_add_u32 s100, s58, 0x8000
	s_addc_u32 s101, s59, 0
	s_add_i32 s99, s98, 0x0
	s_mov_b32 m0, s99
	s_nop 0
	global_load_lds_dwordx4 v68, s[100:101]
	s_add_u32 s100, s58, 0x8000
	s_addc_u32 s101, s59, 0
	s_add_i32 s99, s98, 0x2000
	s_mov_b32 m0, s99
	s_nop 0
	global_load_lds_dwordx4 v69, s[100:101]
	s_add_u32 s100, s28, 0x8000
	s_addc_u32 s101, s29, 0
	s_add_i32 s99, s98, 0x4000
	s_mov_b32 m0, s99
	s_nop 0
	global_load_lds_dwordx4 v68, s[100:101]
	s_add_u32 s100, s28, 0x8000
	s_addc_u32 s101, s29, 0
	s_add_i32 s99, s98, 0x6000
	s_mov_b32 m0, s99
	s_nop 0
	global_load_lds_dwordx4 v69, s[100:101]
	s_waitcnt vmcnt(0)
	s_mov_b64 s[6:7], -1

	.amdhsa_kernel _Z6mk_fwd4Args
		.amdhsa_group_segment_fixed_size 0
		.amdhsa_private_segment_fixed_size 0
		.amdhsa_kernarg_size 448
		.amdhsa_user_sgpr_count 2
		.amdhsa_user_sgpr_dispatch_ptr 0
		.amdhsa_user_sgpr_queue_ptr 0
		.amdhsa_user_sgpr_kernarg_segment_ptr 1
		.amdhsa_user_sgpr_dispatch_id 0
		.amdhsa_user_sgpr_kernarg_preload_length 0
		.amdhsa_user_sgpr_kernarg_preload_offset 0
		.amdhsa_user_sgpr_private_segment_size 0
		.amdhsa_uses_dynamic_stack 0
		.amdhsa_enable_private_segment 0
		.amdhsa_system_sgpr_workgroup_id_x 1
		.amdhsa_system_sgpr_workgroup_id_y 0
		.amdhsa_system_sgpr_workgroup_id_z 0
		.amdhsa_system_sgpr_workgroup_info 0
		.amdhsa_system_vgpr_workitem_id 0
		.amdhsa_next_free_vgpr 255
		.amdhsa_next_free_sgpr 102
		.amdhsa_accum_offset 256
		.amdhsa_reserve_vcc 1
		.amdhsa_float_round_mode_32 0
		.amdhsa_float_round_mode_16_64 0
		.amdhsa_float_denorm_mode_32 3
		.amdhsa_float_denorm_mode_16_64 3
		.amdhsa_dx10_clamp 1
		.amdhsa_ieee_mode 1
		.amdhsa_fp16_overflow 0
		.amdhsa_tg_split 0
		.amdhsa_exception_fp_ieee_invalid_op 0
		.amdhsa_exception_fp_denorm_src 0
		.amdhsa_exception_fp_ieee_div_zero 0
		.amdhsa_exception_fp_ieee_overflow 0
		.amdhsa_exception_fp_ieee_underflow 0
		.amdhsa_exception_fp_ieee_inexact 0
		.amdhsa_exception_int_div_zero 0
	.end_amdhsa_kernel

amdhsa.kernels:
  - .agpr_count:     0
    .args:
      - .offset:         0
        .size:           192
        .value_kind:     by_value
      - .offset:         192
        .size:           4
        .value_kind:     hidden_block_count_x
      - .offset:         196
        .size:           4
        .value_kind:     hidden_block_count_y
      - .offset:         200
        .size:           4
        .value_kind:     hidden_block_count_z
      - .offset:         204
        .size:           2
        .value_kind:     hidden_group_size_x
      - .offset:         206
        .size:           2
        .value_kind:     hidden_group_size_y
      - .offset:         208
        .size:           2
        .value_kind:     hidden_group_size_z
      - .offset:         210
        .size:           2
        .value_kind:     hidden_remainder_x
      - .offset:         212
        .size:           2
        .value_kind:     hidden_remainder_y
      - .offset:         214
        .size:           2
        .value_kind:     hidden_remainder_z
      - .offset:         232
        .size:           8
        .value_kind:     hidden_global_offset_x
      - .offset:         240
        .size:           8
        .value_kind:     hidden_global_offset_y
      - .offset:         248
        .size:           8
        .value_kind:     hidden_global_offset_z
      - .offset:         256
        .size:           2
        .value_kind:     hidden_grid_dims
      - .offset:         312
        .size:           4
        .value_kind:     hidden_dynamic_lds_size
    .group_segment_fixed_size: 0
    .kernarg_segment_align: 8
    .kernarg_segment_size: 448
    .language:       OpenCL C
    .language_version:
      - 2
      - 0
    .max_flat_workgroup_size: 512
    .name:           _Z6mk_fwd4Args
    .private_segment_fixed_size: 0
    .sgpr_count:     108
    .sgpr_spill_count: 20
    .symbol:         _Z6mk_fwd4Args.kd
    .uniform_work_group_size: 1
    .uses_dynamic_stack: false
    .vgpr_count:     255
    .vgpr_spill_count: 0
    .wavefront_size: 64
